# gate phase: next token's three loads prefetched during the current token (loop had load-then-wait per token) + its wave-sum via DPP/permlane
# baseline (speedup 1.0000x reference)
.LBB0_650:
	s_waitcnt vmcnt(4) lgkmcnt(0)
	v_cndmask_b32_e64 v0, 0, 1, s[92:93]
	v_cmp_ne_u32_e64 s[0:1], 1, v0
	v_mov_b32_e32 v9, v174
	s_andn2_b64 vcc, exec, s[92:93]
	v_writelane_b32 v253, s0, 41
	s_barrier
	s_nop 0
	v_writelane_b32 v253, s1, 42
	s_cbranch_vccnz .LBB0_653
	v_readlane_b32 s4, v253, 18
	v_readlane_b32 s5, v253, 19
	v_readlane_b32 s6, v253, 20
	v_readlane_b32 s7, v253, 21
	v_readlane_b32 s8, v253, 22
	v_readlane_b32 s9, v253, 23
	v_readlane_b32 s10, v253, 24
	v_readlane_b32 s11, v253, 25
	v_readlane_b32 s12, v253, 26
	v_readlane_b32 s13, v253, 27
	v_readlane_b32 s14, v253, 28
	v_readlane_b32 s15, v253, 29
	v_readlane_b32 s16, v253, 30
	v_readlane_b32 s17, v253, 31
	v_readlane_b32 s18, v253, 32
	v_readlane_b32 s19, v253, 33
	s_mov_b64 s[0:1], s[4:5]
	s_mov_b64 s[4:5], s[8:9]
	s_mov_b64 s[6:7], s[10:11]
	s_mov_b64 s[8:9], s[12:13]
	s_mov_b64 s[10:11], s[14:15]
	s_mov_b64 s[12:13], s[16:17]
	s_mov_b64 s[14:15], s[18:19]
	v_lshlrev_b32_e32 v10, 3, v9
	v_readlane_b32 s4, v253, 0
	v_mov_b32_e32 v0, s0
	v_mov_b32_e32 v1, s1
	v_ashrrev_i32_e32 v11, 31, v10
	v_readlane_b32 s18, v253, 14
	v_readlane_b32 s19, v253, 15
	v_ashrrev_i32_e32 v2, 3, v9
	v_lshl_add_u64 v[4:5], v[10:11], 2, v[0:1]
	v_mov_b32_e32 v0, s18
	v_mov_b32_e32 v1, s19
	v_ashrrev_i32_e32 v3, 31, v2
	v_lshl_add_u64 v[0:1], v[2:3], 2, v[0:1]
	global_load_dword v8, v[0:1], off
	s_nop 0
	global_load_dwordx4 v[0:3], v[4:5], off offset:16
	s_nop 0
	global_load_dwordx4 v[4:7], v[4:5], off
	v_add_u32_e32 v12, 64, v246
	v_cmp_lt_i32_e32 vcc, v245, v12
	v_readlane_b32 s5, v253, 1
	s_ashr_i32 s81, s80, 31
	v_cndmask_b32_e32 v13, v174, v245, vcc
	v_cmp_lt_i32_e32 vcc, v244, v12
	s_lshl_b64 s[4:5], s[80:81], 11
	v_readlane_b32 s6, v253, 2
	v_cndmask_b32_e32 v14, v174, v244, vcc
	v_cmp_lt_i32_e32 vcc, v243, v12
	v_readlane_b32 s7, v253, 3
	s_add_u32 s4, s66, s4
	v_cndmask_b32_e32 v15, v174, v243, vcc
	v_cmp_lt_i32_e32 vcc, v242, v12
	v_readlane_b32 s11, v253, 7
	v_lshlrev_b32_e32 v18, 2, v13
	v_cndmask_b32_e32 v21, v174, v242, vcc
	v_cmp_lt_i32_e32 vcc, v241, v12
	s_addc_u32 s5, s67, s5
	s_lshl_b64 s[6:7], s[80:81], 9
	v_cndmask_b32_e32 v22, v174, v241, vcc
	v_cmp_lt_i32_e32 vcc, v240, v12
	v_readlane_b32 s8, v253, 4
	v_readlane_b32 s9, v253, 5
	v_cndmask_b32_e32 v12, v174, v240, vcc
	v_lshlrev_b32_e32 v23, 2, v12
	v_lshlrev_b64 v[12:13], 1, v[10:11]
	v_ashrrev_i32_e32 v24, 5, v9
	s_mov_b64 s[0:1], 0x19400400
	s_mov_b32 s11, 0x1800000
	v_lshlrev_b32_e32 v19, 2, v14
	v_lshlrev_b32_e32 v20, 2, v15
	s_ashr_i32 s79, s78, 31
	v_lshl_add_u64 v[10:11], s[4:5], 0, v[12:13]
	v_mov_b64_e32 v[14:15], s[6:7]
	s_lshl_b64 s[8:9], s[80:81], 10
	s_lshl_b64 s[4:5], s[78:79], 11
	s_lshl_b64 s[6:7], s[78:79], 9
	v_lshl_add_u64 v[10:11], v[10:11], 0, s[0:1]
	v_mad_i64_i32 v[14:15], s[0:1], v24, s11, v[14:15]
	v_and_b32_e32 v9, 31, v9
	s_add_u32 s0, s66, s8
	v_readlane_b32 s12, v253, 8
	v_readlane_b32 s13, v253, 9
	v_readlane_b32 s14, v253, 10
	v_readlane_b32 s15, v253, 11
	v_lshl_or_b32 v14, v9, 4, v14
	s_addc_u32 s1, s67, s9
	v_readlane_b32 s10, v253, 6
	s_mov_b64 s[12:13], 0x13400000
	s_mov_b64 s[14:15], 0xd400000
	v_lshl_add_u64 v[14:15], s[66:67], 0, v[14:15]
	v_lshl_add_u64 v[24:25], s[0:1], 0, v[12:13]
	v_mov_b32_e32 v16, 0x3727c5ac
	s_mov_b32 s10, 0xf800000
	v_mov_b32_e32 v17, 0x260
	v_lshlrev_b32_e32 v21, 2, v21
	v_lshlrev_b32_e32 v22, 2, v22
	s_lshl_b64 s[8:9], s[78:79], 10
	v_lshl_add_u64 v[12:13], v[14:15], 0, s[12:13]
	v_lshl_add_u64 v[14:15], v[24:25], 0, s[14:15]
	s_mov_b32 s11, s80
	v_readlane_b32 s16, v253, 12
	v_readlane_b32 s17, v253, 13
	s_waitcnt vmcnt(2)
	v_mov_b32_e32 v9, v8
	v_add_co_u32_e32 v108, vcc, 0xf7000000, v12
	global_load_dwordx4 v[100:103], v[14:15], off
	global_load_dwordx4 v[104:107], v[12:13], off
	v_addc_co_u32_e32 v109, vcc, -1, v13, vcc
	global_load_dwordx4 v[108:111], v[108:109], off
	v_lshl_add_u64 v[14:15], v[14:15], 0, s[8:9]
	v_lshl_add_u64 v[12:13], v[12:13], 0, s[6:7]
	s_waitcnt vmcnt(0)
	s_branch .Lgate_body
.LBB0_652:
	s_waitcnt vmcnt(1)
.Lgate_body:
	v_mov_b64_e32 v[24:25], v[100:101]
	v_mov_b64_e32 v[26:27], v[102:103]
	v_mov_b64_e32 v[28:29], v[104:105]
	v_mov_b64_e32 v[30:31], v[106:107]
	v_mov_b64_e32 v[32:33], v[108:109]
	v_mov_b64_e32 v[34:35], v[110:111]
	s_add_i32 s11, s11, s78
	s_cmp_lt_i32 s11, 0xc000
	s_cbranch_scc0 .Lgate_nopf
	v_add_co_u32_e32 v108, vcc, 0xf7000000, v12
	global_load_dwordx4 v[100:103], v[14:15], off
	global_load_dwordx4 v[104:107], v[12:13], off
	v_addc_co_u32_e32 v109, vcc, -1, v13, vcc
	global_load_dwordx4 v[108:111], v[108:109], off
	v_lshl_add_u64 v[14:15], v[14:15], 0, s[8:9]
	v_lshl_add_u64 v[12:13], v[12:13], 0, s[6:7]
.Lgate_nopf:
	v_lshlrev_b32_e32 v36, 16, v27
	v_and_b32_e32 v37, 0xffff0000, v27
	v_lshlrev_b32_e32 v40, 16, v26
	v_and_b32_e32 v41, 0xffff0000, v26
	v_lshlrev_b32_e32 v38, 16, v31
	v_and_b32_e32 v39, 0xffff0000, v31
	v_lshlrev_b32_e32 v26, 16, v30
	v_and_b32_e32 v27, 0xffff0000, v30
	v_lshlrev_b32_e32 v30, 16, v25
	v_and_b32_e32 v31, 0xffff0000, v25
	v_lshlrev_b32_e32 v42, 16, v29
	v_and_b32_e32 v43, 0xffff0000, v29
	v_lshlrev_b32_e32 v44, 16, v24
	v_and_b32_e32 v45, 0xffff0000, v24
	v_lshlrev_b32_e32 v24, 16, v28
	v_and_b32_e32 v25, 0xffff0000, v28
	v_pk_add_f32 v[28:29], v[36:37], 0 op_sel_hi:[1,0]
	v_pk_add_f32 v[36:37], v[40:41], 0 op_sel_hi:[1,0]
	v_pk_add_f32 v[30:31], v[30:31], 0 op_sel_hi:[1,0]
	v_pk_fma_f32 v[26:27], v[8:9], v[26:27], v[36:37]
	v_lshlrev_b32_e32 v36, 16, v32
	v_and_b32_e32 v37, 0xffff0000, v32
	v_pk_add_f32 v[40:41], v[44:45], 0 op_sel_hi:[1,0]
	v_lshlrev_b32_e32 v44, 16, v35
	v_and_b32_e32 v45, 0xffff0000, v35
	v_pk_fma_f32 v[28:29], v[8:9], v[38:39], v[28:29]
	v_lshlrev_b32_e32 v38, 16, v34
	v_and_b32_e32 v39, 0xffff0000, v34
	v_lshlrev_b32_e32 v34, 16, v33
	v_and_b32_e32 v35, 0xffff0000, v33
	v_mul_f32_e32 v46, 0xbfb8aa3b, v36
	v_mul_f32_e32 v47, 0xbfb8aa3b, v37
	v_pk_fma_f32 v[30:31], v[8:9], v[42:43], v[30:31]
	v_pk_fma_f32 v[24:25], v[8:9], v[24:25], v[40:41]
	v_mul_f32_e32 v40, 0xbfb8aa3b, v38
	v_mul_f32_e32 v41, 0xbfb8aa3b, v39
	v_mul_f32_e32 v42, 0xbfb8aa3b, v34
	v_mul_f32_e32 v43, 0xbfb8aa3b, v35
	v_exp_f32_e32 v46, v46
	v_exp_f32_e32 v47, v47
	v_exp_f32_e32 v40, v40
	v_exp_f32_e32 v41, v41
	v_exp_f32_e32 v42, v42
	v_exp_f32_e32 v43, v43
	v_mul_f32_e32 v32, 0xbfb8aa3b, v44
	v_mul_f32_e32 v33, 0xbfb8aa3b, v45
	v_add_f32_e32 v46, 1.0, v46
	v_add_f32_e32 v47, 1.0, v47
	v_exp_f32_e32 v32, v32
	v_exp_f32_e32 v33, v33
	v_add_f32_e32 v40, 1.0, v40
	v_add_f32_e32 v41, 1.0, v41
	v_add_f32_e32 v42, 1.0, v42
	v_add_f32_e32 v43, 1.0, v43
	v_rcp_f32_e32 v46, v46
	v_rcp_f32_e32 v47, v47
	v_rcp_f32_e32 v40, v40
	v_rcp_f32_e32 v41, v41
	v_rcp_f32_e32 v42, v42
	v_rcp_f32_e32 v43, v43
	v_add_f32_e32 v32, 1.0, v32
	v_add_f32_e32 v33, 1.0, v33
	v_pk_mul_f32 v[36:37], v[46:47], v[36:37]
	v_rcp_f32_e32 v32, v32
	v_rcp_f32_e32 v33, v33
	v_pk_mul_f32 v[38:39], v[40:41], v[38:39]
	v_pk_mul_f32 v[34:35], v[42:43], v[34:35]
	v_pk_mul_f32 v[24:25], v[24:25], v[36:37]
	v_pk_mul_f32 v[26:27], v[26:27], v[38:39]
	v_pk_mul_f32 v[30:31], v[30:31], v[34:35]
	v_pk_mul_f32 v[38:39], v[24:25], v[24:25]
	v_pk_mul_f32 v[36:37], v[30:31], v[30:31]
	v_add_f32_e32 v38, v38, v39
	v_add_f32_e32 v36, v36, v38
	v_pk_mul_f32 v[32:33], v[32:33], v[44:45]
	v_pk_mul_f32 v[34:35], v[26:27], v[26:27]
	v_add_f32_e32 v36, v37, v36
	v_pk_mul_f32 v[28:29], v[28:29], v[32:33]
	v_add_f32_e32 v34, v34, v36
	v_pk_mul_f32 v[32:33], v[28:29], v[28:29]
	v_add_f32_e32 v34, v35, v34
	v_add_f32_e32 v32, v32, v34
	v_add_f32_e32 v32, v33, v32
	s_nop 1
	v_add_f32_dpp v32, v32, v32 quad_perm:[1,0,3,2] row_mask:0xf bank_mask:0xf
	s_nop 1
	v_add_f32_dpp v32, v32, v32 quad_perm:[2,3,0,1] row_mask:0xf bank_mask:0xf
	s_nop 1
	v_add_f32_dpp v32, v32, v32 row_half_mirror row_mask:0xf bank_mask:0xf
	s_nop 1
	v_add_f32_dpp v32, v32, v32 row_mirror row_mask:0xf bank_mask:0xf
	v_mov_b32_e32 v33, v32
	s_nop 1
	v_permlane16_swap_b32_e32 v33, v32
	v_add_f32_e32 v32, v32, v33
	v_mov_b32_e32 v33, v32
	s_nop 1
	v_permlane32_swap_b32_e32 v33, v32
	v_add_f32_e32 v32, v32, v33
	v_fmamk_f32 v32, v32, 0x3b000000, v16
	v_mul_f32_e32 v33, 0x4f800000, v32
	v_cmp_gt_f32_e32 vcc, s10, v32
	s_nop 1
	v_cndmask_b32_e32 v32, v32, v33, vcc
	v_sqrt_f32_e32 v33, v32
	s_nop 0
	v_add_u32_e32 v34, -1, v33
	v_add_u32_e32 v35, 1, v33
	v_fma_f32 v36, -v34, v33, v32
	v_fma_f32 v37, -v35, v33, v32
	v_cmp_ge_f32_e64 s[0:1], 0, v36
	s_nop 1
	v_cndmask_b32_e64 v33, v33, v34, s[0:1]
	v_cmp_lt_f32_e64 s[0:1], 0, v37
	s_nop 1
	v_cndmask_b32_e64 v33, v33, v35, s[0:1]
	v_mul_f32_e32 v34, 0x37800000, v33
	v_cndmask_b32_e32 v33, v33, v34, vcc
	v_cmp_class_f32_e32 vcc, v32, v17
	s_nop 1
	v_cndmask_b32_e32 v32, v33, v32, vcc
	v_div_scale_f32 v33, s[0:1], v32, v32, 1.0
	v_rcp_f32_e32 v35, v33
	v_div_scale_f32 v34, vcc, 1.0, v32, 1.0
	v_fma_f32 v36, -v33, v35, 1.0
	v_fmac_f32_e32 v35, v36, v35
	v_mul_f32_e32 v36, v34, v35
	v_fma_f32 v37, -v33, v36, v34
	v_fmac_f32_e32 v36, v37, v35
	v_fma_f32 v33, -v33, v36, v34
	v_div_fmas_f32 v33, v33, v35, v36
	v_div_fixup_f32 v32, v33, v32, 1.0
	v_pk_mul_f32 v[24:25], v[24:25], v[32:33] op_sel_hi:[1,0]
	v_pk_mul_f32 v[30:31], v[30:31], v[32:33] op_sel_hi:[1,0]
	v_pk_mul_f32 v[26:27], v[26:27], v[32:33] op_sel_hi:[1,0]
	v_pk_mul_f32 v[28:29], v[28:29], v[32:33] op_sel_hi:[1,0]
	v_pk_mul_f32 v[24:25], v[4:5], v[24:25]
	v_pk_mul_f32 v[30:31], v[6:7], v[30:31]
	v_pk_mul_f32 v[26:27], v[0:1], v[26:27]
	v_pk_mul_f32 v[28:29], v[2:3], v[28:29]
	v_cvt_pk_bf16_f32 v24, v24, v25
	v_cvt_pk_bf16_f32 v25, v30, v31
	v_cvt_pk_bf16_f32 v26, v26, v27
	v_cvt_pk_bf16_f32 v27, v28, v29
	global_store_dwordx4 v[10:11], v[24:27], off
	v_lshl_add_u64 v[10:11], v[10:11], 0, s[4:5]
	s_cmp_lt_i32 s11, 0xc000
	s_cbranch_scc1 .LBB0_652
